# P1 silu epilogue: part of the reciprocals on the FMA pipe (bit-trick seed + 3 Newton steps, within 0.5 ulp) to unload the transcendental unit
# speedup vs baseline: 1.0070x; 1.0007x over previous
; __device__ __forceinline__ unsigned cvt_pk_bf16(float lo, float hi) { unsigned r; asm volatile("v_cvt_pk_bf16_f32 %0, %1, %2" : "=v"(r) : "v"(lo), "v"(hi)); return r; }
; __device__ __forceinline__ float silu_f(float x) { return x * __builtin_amdgcn_rcpf(1.0f + __builtin_amdgcn_exp2f(-x * LOG2E)); }
;     __device__ __forceinline__ void operator()(const f32x4 (&acc)[2][2][4][2], const pg8::Unit& u, int wr, int wc, int fr, int fq, const LAS float* tab) const {
;     ...
;                 for (int bj = 0; bj < 2; ++bj) {
;                     f32x4 v0 = acc[ai][bj][m][0], v1 = acc[ai][bj][m][1];
;                     if (kind == 1) {
; #pragma unroll
;                         for (int e = 0; e < 4; ++e) { v0[e] = silu_f(v0[e]); v1[e] = silu_f(v1[e]); }
;                     } else if (kind == 2) { v0 = v0 * QSCALE; v1 = v1 * QSCALE; }
;                     else if (kind == 3) {
; #pragma unroll
;                         for (int e = 0; e < 4; ++e) { s1 += v0[e] + v1[e]; s2 += v0[e] * v0[e] + v1[e] * v1[e]; }
;                     } else if (kind == 4) {
;                         v0 = v0 * f2; v1 = v1 * f2;
; #pragma unroll
;                         for (int e = 0; e < 4; ++e) s2 += v0[e] * v0[e] + v1[e] * v1[e];
;                     }
;                     u32x4 w; w.x = cvt_pk_bf16(v0[0], v0[1]); w.y = cvt_pk_bf16(v0[2], v0[3]); w.z = cvt_pk_bf16(v1[0], v1[1]); w.w = cvt_pk_bf16(v1[2], v1[3]);
;                     *(u32x4*)(rowp + bj * bjstep) = w;
.Lepi_silu:
	v_mov_b32_e32 v220, 0xbfb8aa3b
	v_mov_b32_e32 v221, 0xbfb8aa3b
	v_mov_b32_e32 v222, 1.0
	v_mov_b32_e32 v223, 1.0
	v_pk_mul_f32 v[224:225], v[126:127], v[220:221]
	v_pk_mul_f32 v[226:227], v[128:129], v[220:221]
	v_pk_mul_f32 v[228:229], v[122:123], v[220:221]
	v_pk_mul_f32 v[230:231], v[124:125], v[220:221]
	v_min_f32_e32 v224, 0x42fc0000, v224
	v_min_f32_e32 v225, 0x42fc0000, v225
	v_min_f32_e32 v226, 0x42fc0000, v226
	v_min_f32_e32 v227, 0x42fc0000, v227
	v_min_f32_e32 v228, 0x42fc0000, v228
	v_min_f32_e32 v229, 0x42fc0000, v229
	v_exp_f32_e32 v224, v224
	v_exp_f32_e32 v225, v225
	v_exp_f32_e32 v226, v226
	v_exp_f32_e32 v227, v227
	v_exp_f32_e32 v228, v228
	v_exp_f32_e32 v229, v229
	v_exp_f32_e32 v230, v230
	v_exp_f32_e32 v231, v231
	v_pk_add_f32 v[224:225], v[224:225], v[222:223]
	v_pk_add_f32 v[226:227], v[226:227], v[222:223]
	v_pk_add_f32 v[228:229], v[228:229], v[222:223]
	v_pk_add_f32 v[230:231], v[230:231], v[222:223]
	v_rcp_f32_e32 v230, v230
	v_rcp_f32_e32 v231, v231
	v_sub_u32_e32 v240, 0x7ef311c7, v224
	v_sub_u32_e32 v241, 0x7ef311c7, v225
	v_sub_u32_e32 v242, 0x7ef311c7, v226
	v_sub_u32_e32 v243, 0x7ef311c7, v227
	v_sub_u32_e32 v244, 0x7ef311c7, v228
	v_sub_u32_e32 v245, 0x7ef311c7, v229
	v_pk_fma_f32 v[246:247], v[224:225], v[240:241], v[222:223] neg_lo:[1,0,0] neg_hi:[1,0,0]
	v_pk_fma_f32 v[248:249], v[226:227], v[242:243], v[222:223] neg_lo:[1,0,0] neg_hi:[1,0,0]
	v_pk_fma_f32 v[250:251], v[228:229], v[244:245], v[222:223] neg_lo:[1,0,0] neg_hi:[1,0,0]
	v_pk_fma_f32 v[240:241], v[240:241], v[246:247], v[240:241]
	v_pk_fma_f32 v[242:243], v[242:243], v[248:249], v[242:243]
	v_pk_fma_f32 v[244:245], v[244:245], v[250:251], v[244:245]
	v_pk_fma_f32 v[246:247], v[224:225], v[240:241], v[222:223] neg_lo:[1,0,0] neg_hi:[1,0,0]
	v_pk_fma_f32 v[248:249], v[226:227], v[242:243], v[222:223] neg_lo:[1,0,0] neg_hi:[1,0,0]
	v_pk_fma_f32 v[250:251], v[228:229], v[244:245], v[222:223] neg_lo:[1,0,0] neg_hi:[1,0,0]
	v_pk_fma_f32 v[240:241], v[240:241], v[246:247], v[240:241]
	v_pk_fma_f32 v[242:243], v[242:243], v[248:249], v[242:243]
	v_pk_fma_f32 v[244:245], v[244:245], v[250:251], v[244:245]
	v_pk_fma_f32 v[246:247], v[224:225], v[240:241], v[222:223] neg_lo:[1,0,0] neg_hi:[1,0,0]
	v_pk_fma_f32 v[248:249], v[226:227], v[242:243], v[222:223] neg_lo:[1,0,0] neg_hi:[1,0,0]
	v_pk_fma_f32 v[250:251], v[228:229], v[244:245], v[222:223] neg_lo:[1,0,0] neg_hi:[1,0,0]
	v_pk_fma_f32 v[240:241], v[240:241], v[246:247], v[240:241]
	v_pk_fma_f32 v[242:243], v[242:243], v[248:249], v[242:243]
	v_pk_fma_f32 v[244:245], v[244:245], v[250:251], v[244:245]
	v_pk_mul_f32 v[126:127], v[126:127], v[240:241]
	v_pk_mul_f32 v[128:129], v[128:129], v[242:243]
	v_pk_mul_f32 v[122:123], v[122:123], v[244:245]
	v_pk_mul_f32 v[124:125], v[124:125], v[230:231]
	v_cvt_pk_bf16_f32 v232, v126, v127
	v_cvt_pk_bf16_f32 v233, v128, v129
	v_cvt_pk_bf16_f32 v234, v122, v123
	v_cvt_pk_bf16_f32 v235, v124, v125
	global_store_dwordx4 v218, v[232:235], s[96:97]
	s_add_u32 s96, s96, 0x1000
	s_addc_u32 s97, s97, 0
	v_pk_mul_f32 v[224:225], v[118:119], v[220:221]
	v_pk_mul_f32 v[226:227], v[120:121], v[220:221]
	v_pk_mul_f32 v[228:229], v[114:115], v[220:221]
	v_pk_mul_f32 v[230:231], v[116:117], v[220:221]
	v_min_f32_e32 v224, 0x42fc0000, v224
	v_min_f32_e32 v225, 0x42fc0000, v225
	v_min_f32_e32 v226, 0x42fc0000, v226
	v_min_f32_e32 v227, 0x42fc0000, v227
	v_exp_f32_e32 v224, v224
	v_exp_f32_e32 v225, v225
	v_exp_f32_e32 v226, v226
	v_exp_f32_e32 v227, v227
	v_exp_f32_e32 v228, v228
	v_exp_f32_e32 v229, v229
	v_exp_f32_e32 v230, v230
	v_exp_f32_e32 v231, v231
	v_pk_add_f32 v[224:225], v[224:225], v[222:223]
	v_pk_add_f32 v[226:227], v[226:227], v[222:223]
	v_pk_add_f32 v[228:229], v[228:229], v[222:223]
	v_pk_add_f32 v[230:231], v[230:231], v[222:223]
	v_rcp_f32_e32 v228, v228
	v_rcp_f32_e32 v229, v229
	v_rcp_f32_e32 v230, v230
	v_rcp_f32_e32 v231, v231
	v_sub_u32_e32 v240, 0x7ef311c7, v224
	v_sub_u32_e32 v241, 0x7ef311c7, v225
	v_sub_u32_e32 v242, 0x7ef311c7, v226
	v_sub_u32_e32 v243, 0x7ef311c7, v227
	v_pk_fma_f32 v[246:247], v[224:225], v[240:241], v[222:223] neg_lo:[1,0,0] neg_hi:[1,0,0]
	v_pk_fma_f32 v[248:249], v[226:227], v[242:243], v[222:223] neg_lo:[1,0,0] neg_hi:[1,0,0]
	v_pk_fma_f32 v[240:241], v[240:241], v[246:247], v[240:241]
	v_pk_fma_f32 v[242:243], v[242:243], v[248:249], v[242:243]
	v_pk_fma_f32 v[246:247], v[224:225], v[240:241], v[222:223] neg_lo:[1,0,0] neg_hi:[1,0,0]
	v_pk_fma_f32 v[248:249], v[226:227], v[242:243], v[222:223] neg_lo:[1,0,0] neg_hi:[1,0,0]
	v_pk_fma_f32 v[240:241], v[240:241], v[246:247], v[240:241]
	v_pk_fma_f32 v[242:243], v[242:243], v[248:249], v[242:243]
	v_pk_fma_f32 v[246:247], v[224:225], v[240:241], v[222:223] neg_lo:[1,0,0] neg_hi:[1,0,0]
	v_pk_fma_f32 v[248:249], v[226:227], v[242:243], v[222:223] neg_lo:[1,0,0] neg_hi:[1,0,0]
	v_pk_fma_f32 v[240:241], v[240:241], v[246:247], v[240:241]
	v_pk_fma_f32 v[242:243], v[242:243], v[248:249], v[242:243]
	v_pk_mul_f32 v[118:119], v[118:119], v[240:241]
	v_pk_mul_f32 v[120:121], v[120:121], v[242:243]
	v_pk_mul_f32 v[114:115], v[114:115], v[228:229]
	v_pk_mul_f32 v[116:117], v[116:117], v[230:231]
	v_cvt_pk_bf16_f32 v236, v118, v119
	v_cvt_pk_bf16_f32 v237, v120, v121
	v_cvt_pk_bf16_f32 v238, v114, v115
	v_cvt_pk_bf16_f32 v239, v116, v117
	global_store_dwordx4 v218, v[236:239], s[96:97]
	s_add_u32 s96, s96, 0x1000
	s_addc_u32 s97, s97, 0
	v_pk_mul_f32 v[224:225], v[110:111], v[220:221]
	v_pk_mul_f32 v[226:227], v[112:113], v[220:221]
	v_pk_mul_f32 v[228:229], v[106:107], v[220:221]
	v_pk_mul_f32 v[230:231], v[108:109], v[220:221]
	v_min_f32_e32 v224, 0x42fc0000, v224
; __device__ __forceinline__ unsigned cvt_pk_bf16(float lo, float hi) { unsigned r; asm volatile("v_cvt_pk_bf16_f32 %0, %1, %2" : "=v"(r) : "v"(lo), "v"(hi)); return r; }
; __device__ __forceinline__ float silu_f(float x) { return x * __builtin_amdgcn_rcpf(1.0f + __builtin_amdgcn_exp2f(-x * LOG2E)); }
;     __device__ __forceinline__ void operator()(const f32x4 (&acc)[2][2][4][2], const pg8::Unit& u, int wr, int wc, int fr, int fq, const LAS float* tab) const {
;     ...
;                 for (int bj = 0; bj < 2; ++bj) {
;                     f32x4 v0 = acc[ai][bj][m][0], v1 = acc[ai][bj][m][1];
;                     if (kind == 1) {
; #pragma unroll
;                         for (int e = 0; e < 4; ++e) { v0[e] = silu_f(v0[e]); v1[e] = silu_f(v1[e]); }
;                     } else if (kind == 2) { v0 = v0 * QSCALE; v1 = v1 * QSCALE; }
;                     else if (kind == 3) {
; #pragma unroll
;                         for (int e = 0; e < 4; ++e) { s1 += v0[e] + v1[e]; s2 += v0[e] * v0[e] + v1[e] * v1[e]; }
;                     } else if (kind == 4) {
;                         v0 = v0 * f2; v1 = v1 * f2;
; #pragma unroll
;                         for (int e = 0; e < 4; ++e) s2 += v0[e] * v0[e] + v1[e] * v1[e];
;                     }
;                     u32x4 w; w.x = cvt_pk_bf16(v0[0], v0[1]); w.y = cvt_pk_bf16(v0[2], v0[3]); w.z = cvt_pk_bf16(v1[0], v1[1]); w.w = cvt_pk_bf16(v1[2], v1[3]);
;                     *(u32x4*)(rowp + bj * bjstep) = w;
	v_min_f32_e32 v225, 0x42fc0000, v225
	v_min_f32_e32 v226, 0x42fc0000, v226
	v_min_f32_e32 v227, 0x42fc0000, v227
	v_min_f32_e32 v228, 0x42fc0000, v228
	v_min_f32_e32 v229, 0x42fc0000, v229
	v_exp_f32_e32 v224, v224
	v_exp_f32_e32 v225, v225
	v_exp_f32_e32 v226, v226
	v_exp_f32_e32 v227, v227
	v_exp_f32_e32 v228, v228
	v_exp_f32_e32 v229, v229
	v_exp_f32_e32 v230, v230
	v_exp_f32_e32 v231, v231
	v_pk_add_f32 v[224:225], v[224:225], v[222:223]
	v_pk_add_f32 v[226:227], v[226:227], v[222:223]
	v_pk_add_f32 v[228:229], v[228:229], v[222:223]
	v_pk_add_f32 v[230:231], v[230:231], v[222:223]
	v_rcp_f32_e32 v230, v230
	v_rcp_f32_e32 v231, v231
	v_sub_u32_e32 v240, 0x7ef311c7, v224
	v_sub_u32_e32 v241, 0x7ef311c7, v225
	v_sub_u32_e32 v242, 0x7ef311c7, v226
	v_sub_u32_e32 v243, 0x7ef311c7, v227
	v_sub_u32_e32 v244, 0x7ef311c7, v228
	v_sub_u32_e32 v245, 0x7ef311c7, v229
	v_pk_fma_f32 v[246:247], v[224:225], v[240:241], v[222:223] neg_lo:[1,0,0] neg_hi:[1,0,0]
	v_pk_fma_f32 v[248:249], v[226:227], v[242:243], v[222:223] neg_lo:[1,0,0] neg_hi:[1,0,0]
	v_pk_fma_f32 v[250:251], v[228:229], v[244:245], v[222:223] neg_lo:[1,0,0] neg_hi:[1,0,0]
	v_pk_fma_f32 v[240:241], v[240:241], v[246:247], v[240:241]
	v_pk_fma_f32 v[242:243], v[242:243], v[248:249], v[242:243]
	v_pk_fma_f32 v[244:245], v[244:245], v[250:251], v[244:245]
	v_pk_fma_f32 v[246:247], v[224:225], v[240:241], v[222:223] neg_lo:[1,0,0] neg_hi:[1,0,0]
	v_pk_fma_f32 v[248:249], v[226:227], v[242:243], v[222:223] neg_lo:[1,0,0] neg_hi:[1,0,0]
	v_pk_fma_f32 v[250:251], v[228:229], v[244:245], v[222:223] neg_lo:[1,0,0] neg_hi:[1,0,0]
	v_pk_fma_f32 v[240:241], v[240:241], v[246:247], v[240:241]
	v_pk_fma_f32 v[242:243], v[242:243], v[248:249], v[242:243]
	v_pk_fma_f32 v[244:245], v[244:245], v[250:251], v[244:245]
	v_pk_fma_f32 v[246:247], v[224:225], v[240:241], v[222:223] neg_lo:[1,0,0] neg_hi:[1,0,0]
	v_pk_fma_f32 v[248:249], v[226:227], v[242:243], v[222:223] neg_lo:[1,0,0] neg_hi:[1,0,0]
	v_pk_fma_f32 v[250:251], v[228:229], v[244:245], v[222:223] neg_lo:[1,0,0] neg_hi:[1,0,0]
	v_pk_fma_f32 v[240:241], v[240:241], v[246:247], v[240:241]
	v_pk_fma_f32 v[242:243], v[242:243], v[248:249], v[242:243]
	v_pk_fma_f32 v[244:245], v[244:245], v[250:251], v[244:245]
	v_pk_mul_f32 v[110:111], v[110:111], v[240:241]
	v_pk_mul_f32 v[112:113], v[112:113], v[242:243]
	v_pk_mul_f32 v[106:107], v[106:107], v[244:245]
	v_pk_mul_f32 v[108:109], v[108:109], v[230:231]
	v_cvt_pk_bf16_f32 v232, v110, v111
	v_cvt_pk_bf16_f32 v233, v112, v113
	v_cvt_pk_bf16_f32 v234, v106, v107
	v_cvt_pk_bf16_f32 v235, v108, v109
	global_store_dwordx4 v218, v[232:235], s[96:97]
	s_add_u32 s96, s96, 0x1000
	s_addc_u32 s97, s97, 0
	v_pk_mul_f32 v[224:225], v[102:103], v[220:221]
	v_pk_mul_f32 v[226:227], v[104:105], v[220:221]
	v_pk_mul_f32 v[228:229], v[98:99], v[220:221]
	v_pk_mul_f32 v[230:231], v[100:101], v[220:221]
	v_min_f32_e32 v224, 0x42fc0000, v224
	v_min_f32_e32 v225, 0x42fc0000, v225
	v_min_f32_e32 v226, 0x42fc0000, v226
	v_min_f32_e32 v227, 0x42fc0000, v227
	v_exp_f32_e32 v224, v224
	v_exp_f32_e32 v225, v225
	v_exp_f32_e32 v226, v226
	v_exp_f32_e32 v227, v227
	v_exp_f32_e32 v228, v228
	v_exp_f32_e32 v229, v229
	v_exp_f32_e32 v230, v230
	v_exp_f32_e32 v231, v231
	v_pk_add_f32 v[224:225], v[224:225], v[222:223]
	v_pk_add_f32 v[226:227], v[226:227], v[222:223]
	v_pk_add_f32 v[228:229], v[228:229], v[222:223]
	v_pk_add_f32 v[230:231], v[230:231], v[222:223]
	v_rcp_f32_e32 v228, v228
	v_rcp_f32_e32 v229, v229
	v_rcp_f32_e32 v230, v230
	v_rcp_f32_e32 v231, v231
	v_sub_u32_e32 v240, 0x7ef311c7, v224
	v_sub_u32_e32 v241, 0x7ef311c7, v225
	v_sub_u32_e32 v242, 0x7ef311c7, v226
	v_sub_u32_e32 v243, 0x7ef311c7, v227
	v_pk_fma_f32 v[246:247], v[224:225], v[240:241], v[222:223] neg_lo:[1,0,0] neg_hi:[1,0,0]
	v_pk_fma_f32 v[248:249], v[226:227], v[242:243], v[222:223] neg_lo:[1,0,0] neg_hi:[1,0,0]
	v_pk_fma_f32 v[240:241], v[240:241], v[246:247], v[240:241]
	v_pk_fma_f32 v[242:243], v[242:243], v[248:249], v[242:243]
	v_pk_fma_f32 v[246:247], v[224:225], v[240:241], v[222:223] neg_lo:[1,0,0] neg_hi:[1,0,0]
	v_pk_fma_f32 v[248:249], v[226:227], v[242:243], v[222:223] neg_lo:[1,0,0] neg_hi:[1,0,0]
	v_pk_fma_f32 v[240:241], v[240:241], v[246:247], v[240:241]
	v_pk_fma_f32 v[242:243], v[242:243], v[248:249], v[242:243]
	v_pk_fma_f32 v[246:247], v[224:225], v[240:241], v[222:223] neg_lo:[1,0,0] neg_hi:[1,0,0]
	v_pk_fma_f32 v[248:249], v[226:227], v[242:243], v[222:223] neg_lo:[1,0,0] neg_hi:[1,0,0]
	v_pk_fma_f32 v[240:241], v[240:241], v[246:247], v[240:241]
	v_pk_fma_f32 v[242:243], v[242:243], v[248:249], v[242:243]
	v_pk_mul_f32 v[102:103], v[102:103], v[240:241]
	v_pk_mul_f32 v[104:105], v[104:105], v[242:243]
	v_pk_mul_f32 v[98:99], v[98:99], v[228:229]
	v_pk_mul_f32 v[100:101], v[100:101], v[230:231]
	v_cvt_pk_bf16_f32 v236, v102, v103
	v_cvt_pk_bf16_f32 v237, v104, v105
	v_cvt_pk_bf16_f32 v238, v98, v99
	v_cvt_pk_bf16_f32 v239, v100, v101
	global_store_dwordx4 v218, v[236:239], s[96:97]
	s_add_u32 s96, s96, 0x1000
	s_addc_u32 s97, s97, 0
	v_pk_mul_f32 v[224:225], v[94:95], v[220:221]
	v_pk_mul_f32 v[226:227], v[96:97], v[220:221]
	v_pk_mul_f32 v[228:229], v[90:91], v[220:221]
	v_pk_mul_f32 v[230:231], v[92:93], v[220:221]
	v_min_f32_e32 v224, 0x42fc0000, v224
	v_min_f32_e32 v225, 0x42fc0000, v225
	v_min_f32_e32 v226, 0x42fc0000, v226
	v_min_f32_e32 v227, 0x42fc0000, v227
	v_min_f32_e32 v228, 0x42fc0000, v228
	v_min_f32_e32 v229, 0x42fc0000, v229
	v_exp_f32_e32 v224, v224
	v_exp_f32_e32 v225, v225
	v_exp_f32_e32 v226, v226
	v_exp_f32_e32 v227, v227
	v_exp_f32_e32 v228, v228
	v_exp_f32_e32 v229, v229
	v_exp_f32_e32 v230, v230
; __device__ __forceinline__ unsigned cvt_pk_bf16(float lo, float hi) { unsigned r; asm volatile("v_cvt_pk_bf16_f32 %0, %1, %2" : "=v"(r) : "v"(lo), "v"(hi)); return r; }
; __device__ __forceinline__ float silu_f(float x) { return x * __builtin_amdgcn_rcpf(1.0f + __builtin_amdgcn_exp2f(-x * LOG2E)); }
;     __device__ __forceinline__ void operator()(const f32x4 (&acc)[2][2][4][2], const pg8::Unit& u, int wr, int wc, int fr, int fq, const LAS float* tab) const {
;     ...
;                 for (int bj = 0; bj < 2; ++bj) {
;                     f32x4 v0 = acc[ai][bj][m][0], v1 = acc[ai][bj][m][1];
;                     if (kind == 1) {
; #pragma unroll
;                         for (int e = 0; e < 4; ++e) { v0[e] = silu_f(v0[e]); v1[e] = silu_f(v1[e]); }
;                     } else if (kind == 2) { v0 = v0 * QSCALE; v1 = v1 * QSCALE; }
;                     else if (kind == 3) {
; #pragma unroll
;                         for (int e = 0; e < 4; ++e) { s1 += v0[e] + v1[e]; s2 += v0[e] * v0[e] + v1[e] * v1[e]; }
;                     } else if (kind == 4) {
;                         v0 = v0 * f2; v1 = v1 * f2;
; #pragma unroll
;                         for (int e = 0; e < 4; ++e) s2 += v0[e] * v0[e] + v1[e] * v1[e];
;                     }
;                     u32x4 w; w.x = cvt_pk_bf16(v0[0], v0[1]); w.y = cvt_pk_bf16(v0[2], v0[3]); w.z = cvt_pk_bf16(v1[0], v1[1]); w.w = cvt_pk_bf16(v1[2], v1[3]);
;                     *(u32x4*)(rowp + bj * bjstep) = w;
	v_exp_f32_e32 v231, v231
	v_pk_add_f32 v[224:225], v[224:225], v[222:223]
	v_pk_add_f32 v[226:227], v[226:227], v[222:223]
	v_pk_add_f32 v[228:229], v[228:229], v[222:223]
	v_pk_add_f32 v[230:231], v[230:231], v[222:223]
	v_rcp_f32_e32 v230, v230
	v_rcp_f32_e32 v231, v231
	v_sub_u32_e32 v240, 0x7ef311c7, v224
	v_sub_u32_e32 v241, 0x7ef311c7, v225
	v_sub_u32_e32 v242, 0x7ef311c7, v226
	v_sub_u32_e32 v243, 0x7ef311c7, v227
	v_sub_u32_e32 v244, 0x7ef311c7, v228
	v_sub_u32_e32 v245, 0x7ef311c7, v229
	v_pk_fma_f32 v[246:247], v[224:225], v[240:241], v[222:223] neg_lo:[1,0,0] neg_hi:[1,0,0]
	v_pk_fma_f32 v[248:249], v[226:227], v[242:243], v[222:223] neg_lo:[1,0,0] neg_hi:[1,0,0]
	v_pk_fma_f32 v[250:251], v[228:229], v[244:245], v[222:223] neg_lo:[1,0,0] neg_hi:[1,0,0]
	v_pk_fma_f32 v[240:241], v[240:241], v[246:247], v[240:241]
	v_pk_fma_f32 v[242:243], v[242:243], v[248:249], v[242:243]
	v_pk_fma_f32 v[244:245], v[244:245], v[250:251], v[244:245]
	v_pk_fma_f32 v[246:247], v[224:225], v[240:241], v[222:223] neg_lo:[1,0,0] neg_hi:[1,0,0]
	v_pk_fma_f32 v[248:249], v[226:227], v[242:243], v[222:223] neg_lo:[1,0,0] neg_hi:[1,0,0]
	v_pk_fma_f32 v[250:251], v[228:229], v[244:245], v[222:223] neg_lo:[1,0,0] neg_hi:[1,0,0]
	v_pk_fma_f32 v[240:241], v[240:241], v[246:247], v[240:241]
	v_pk_fma_f32 v[242:243], v[242:243], v[248:249], v[242:243]
	v_pk_fma_f32 v[244:245], v[244:245], v[250:251], v[244:245]
	v_pk_fma_f32 v[246:247], v[224:225], v[240:241], v[222:223] neg_lo:[1,0,0] neg_hi:[1,0,0]
	v_pk_fma_f32 v[248:249], v[226:227], v[242:243], v[222:223] neg_lo:[1,0,0] neg_hi:[1,0,0]
	v_pk_fma_f32 v[250:251], v[228:229], v[244:245], v[222:223] neg_lo:[1,0,0] neg_hi:[1,0,0]
	v_pk_fma_f32 v[240:241], v[240:241], v[246:247], v[240:241]
	v_pk_fma_f32 v[242:243], v[242:243], v[248:249], v[242:243]
	v_pk_fma_f32 v[244:245], v[244:245], v[250:251], v[244:245]
	v_pk_mul_f32 v[94:95], v[94:95], v[240:241]
	v_pk_mul_f32 v[96:97], v[96:97], v[242:243]
	v_pk_mul_f32 v[90:91], v[90:91], v[244:245]
	v_pk_mul_f32 v[92:93], v[92:93], v[230:231]
	v_cvt_pk_bf16_f32 v232, v94, v95
	v_cvt_pk_bf16_f32 v233, v96, v97
	v_cvt_pk_bf16_f32 v234, v90, v91
	v_cvt_pk_bf16_f32 v235, v92, v93
	global_store_dwordx4 v218, v[232:235], s[96:97]
	s_add_u32 s96, s96, 0x1000
	s_addc_u32 s97, s97, 0
	v_pk_mul_f32 v[224:225], v[86:87], v[220:221]
	v_pk_mul_f32 v[226:227], v[88:89], v[220:221]
	v_pk_mul_f32 v[228:229], v[82:83], v[220:221]
	v_pk_mul_f32 v[230:231], v[84:85], v[220:221]
	v_min_f32_e32 v224, 0x42fc0000, v224
	v_min_f32_e32 v225, 0x42fc0000, v225
	v_min_f32_e32 v226, 0x42fc0000, v226
	v_min_f32_e32 v227, 0x42fc0000, v227
	v_exp_f32_e32 v224, v224
	v_exp_f32_e32 v225, v225
	v_exp_f32_e32 v226, v226
	v_exp_f32_e32 v227, v227
	v_exp_f32_e32 v228, v228
	v_exp_f32_e32 v229, v229
	v_exp_f32_e32 v230, v230
	v_exp_f32_e32 v231, v231
	v_pk_add_f32 v[224:225], v[224:225], v[222:223]
	v_pk_add_f32 v[226:227], v[226:227], v[222:223]
	v_pk_add_f32 v[228:229], v[228:229], v[222:223]
	v_pk_add_f32 v[230:231], v[230:231], v[222:223]
	v_rcp_f32_e32 v228, v228
	v_rcp_f32_e32 v229, v229
	v_rcp_f32_e32 v230, v230
	v_rcp_f32_e32 v231, v231
	v_sub_u32_e32 v240, 0x7ef311c7, v224
	v_sub_u32_e32 v241, 0x7ef311c7, v225
	v_sub_u32_e32 v242, 0x7ef311c7, v226
	v_sub_u32_e32 v243, 0x7ef311c7, v227
	v_pk_fma_f32 v[246:247], v[224:225], v[240:241], v[222:223] neg_lo:[1,0,0] neg_hi:[1,0,0]
	v_pk_fma_f32 v[248:249], v[226:227], v[242:243], v[222:223] neg_lo:[1,0,0] neg_hi:[1,0,0]
	v_pk_fma_f32 v[240:241], v[240:241], v[246:247], v[240:241]
	v_pk_fma_f32 v[242:243], v[242:243], v[248:249], v[242:243]
	v_pk_fma_f32 v[246:247], v[224:225], v[240:241], v[222:223] neg_lo:[1,0,0] neg_hi:[1,0,0]
	v_pk_fma_f32 v[248:249], v[226:227], v[242:243], v[222:223] neg_lo:[1,0,0] neg_hi:[1,0,0]
	v_pk_fma_f32 v[240:241], v[240:241], v[246:247], v[240:241]
	v_pk_fma_f32 v[242:243], v[242:243], v[248:249], v[242:243]
	v_pk_fma_f32 v[246:247], v[224:225], v[240:241], v[222:223] neg_lo:[1,0,0] neg_hi:[1,0,0]
	v_pk_fma_f32 v[248:249], v[226:227], v[242:243], v[222:223] neg_lo:[1,0,0] neg_hi:[1,0,0]
	v_pk_fma_f32 v[240:241], v[240:241], v[246:247], v[240:241]
	v_pk_fma_f32 v[242:243], v[242:243], v[248:249], v[242:243]
	v_pk_mul_f32 v[86:87], v[86:87], v[240:241]
	v_pk_mul_f32 v[88:89], v[88:89], v[242:243]
	v_pk_mul_f32 v[82:83], v[82:83], v[228:229]
	v_pk_mul_f32 v[84:85], v[84:85], v[230:231]
	v_cvt_pk_bf16_f32 v236, v86, v87
	v_cvt_pk_bf16_f32 v237, v88, v89
	v_cvt_pk_bf16_f32 v238, v82, v83
	v_cvt_pk_bf16_f32 v239, v84, v85
	global_store_dwordx4 v218, v[236:239], s[96:97]
	s_add_u32 s96, s96, 0x1000
	s_addc_u32 s97, s97, 0
	v_pk_mul_f32 v[224:225], v[78:79], v[220:221]
	v_pk_mul_f32 v[226:227], v[80:81], v[220:221]
	v_pk_mul_f32 v[228:229], v[74:75], v[220:221]
	v_pk_mul_f32 v[230:231], v[76:77], v[220:221]
	v_min_f32_e32 v224, 0x42fc0000, v224
	v_min_f32_e32 v225, 0x42fc0000, v225
	v_min_f32_e32 v226, 0x42fc0000, v226
	v_min_f32_e32 v227, 0x42fc0000, v227
	v_min_f32_e32 v228, 0x42fc0000, v228
	v_min_f32_e32 v229, 0x42fc0000, v229
	v_exp_f32_e32 v224, v224
	v_exp_f32_e32 v225, v225
	v_exp_f32_e32 v226, v226
	v_exp_f32_e32 v227, v227
	v_exp_f32_e32 v228, v228
	v_exp_f32_e32 v229, v229
	v_exp_f32_e32 v230, v230
	v_exp_f32_e32 v231, v231
	v_pk_add_f32 v[224:225], v[224:225], v[222:223]
	v_pk_add_f32 v[226:227], v[226:227], v[222:223]
	v_pk_add_f32 v[228:229], v[228:229], v[222:223]
	v_pk_add_f32 v[230:231], v[230:231], v[222:223]
	v_rcp_f32_e32 v230, v230
	v_rcp_f32_e32 v231, v231
	v_sub_u32_e32 v240, 0x7ef311c7, v224
	v_sub_u32_e32 v241, 0x7ef311c7, v225
	v_sub_u32_e32 v242, 0x7ef311c7, v226
	v_sub_u32_e32 v243, 0x7ef311c7, v227
; __device__ __forceinline__ unsigned cvt_pk_bf16(float lo, float hi) { unsigned r; asm volatile("v_cvt_pk_bf16_f32 %0, %1, %2" : "=v"(r) : "v"(lo), "v"(hi)); return r; }
; __device__ __forceinline__ float silu_f(float x) { return x * __builtin_amdgcn_rcpf(1.0f + __builtin_amdgcn_exp2f(-x * LOG2E)); }
;     __device__ __forceinline__ void operator()(const f32x4 (&acc)[2][2][4][2], const pg8::Unit& u, int wr, int wc, int fr, int fq, const LAS float* tab) const {
;     ...
;                 for (int bj = 0; bj < 2; ++bj) {
;                     f32x4 v0 = acc[ai][bj][m][0], v1 = acc[ai][bj][m][1];
;                     if (kind == 1) {
; #pragma unroll
;                         for (int e = 0; e < 4; ++e) { v0[e] = silu_f(v0[e]); v1[e] = silu_f(v1[e]); }
;                     } else if (kind == 2) { v0 = v0 * QSCALE; v1 = v1 * QSCALE; }
;                     else if (kind == 3) {
; #pragma unroll
;                         for (int e = 0; e < 4; ++e) { s1 += v0[e] + v1[e]; s2 += v0[e] * v0[e] + v1[e] * v1[e]; }
;                     } else if (kind == 4) {
;                         v0 = v0 * f2; v1 = v1 * f2;
; #pragma unroll
;                         for (int e = 0; e < 4; ++e) s2 += v0[e] * v0[e] + v1[e] * v1[e];
;                     }
;                     u32x4 w; w.x = cvt_pk_bf16(v0[0], v0[1]); w.y = cvt_pk_bf16(v0[2], v0[3]); w.z = cvt_pk_bf16(v1[0], v1[1]); w.w = cvt_pk_bf16(v1[2], v1[3]);
;                     *(u32x4*)(rowp + bj * bjstep) = w;
	v_sub_u32_e32 v244, 0x7ef311c7, v228
	v_sub_u32_e32 v245, 0x7ef311c7, v229
	v_pk_fma_f32 v[246:247], v[224:225], v[240:241], v[222:223] neg_lo:[1,0,0] neg_hi:[1,0,0]
	v_pk_fma_f32 v[248:249], v[226:227], v[242:243], v[222:223] neg_lo:[1,0,0] neg_hi:[1,0,0]
	v_pk_fma_f32 v[250:251], v[228:229], v[244:245], v[222:223] neg_lo:[1,0,0] neg_hi:[1,0,0]
	v_pk_fma_f32 v[240:241], v[240:241], v[246:247], v[240:241]
	v_pk_fma_f32 v[242:243], v[242:243], v[248:249], v[242:243]
	v_pk_fma_f32 v[244:245], v[244:245], v[250:251], v[244:245]
	v_pk_fma_f32 v[246:247], v[224:225], v[240:241], v[222:223] neg_lo:[1,0,0] neg_hi:[1,0,0]
	v_pk_fma_f32 v[248:249], v[226:227], v[242:243], v[222:223] neg_lo:[1,0,0] neg_hi:[1,0,0]
	v_pk_fma_f32 v[250:251], v[228:229], v[244:245], v[222:223] neg_lo:[1,0,0] neg_hi:[1,0,0]
	v_pk_fma_f32 v[240:241], v[240:241], v[246:247], v[240:241]
	v_pk_fma_f32 v[242:243], v[242:243], v[248:249], v[242:243]
	v_pk_fma_f32 v[244:245], v[244:245], v[250:251], v[244:245]
	v_pk_fma_f32 v[246:247], v[224:225], v[240:241], v[222:223] neg_lo:[1,0,0] neg_hi:[1,0,0]
	v_pk_fma_f32 v[248:249], v[226:227], v[242:243], v[222:223] neg_lo:[1,0,0] neg_hi:[1,0,0]
	v_pk_fma_f32 v[250:251], v[228:229], v[244:245], v[222:223] neg_lo:[1,0,0] neg_hi:[1,0,0]
	v_pk_fma_f32 v[240:241], v[240:241], v[246:247], v[240:241]
	v_pk_fma_f32 v[242:243], v[242:243], v[248:249], v[242:243]
	v_pk_fma_f32 v[244:245], v[244:245], v[250:251], v[244:245]
	v_pk_mul_f32 v[78:79], v[78:79], v[240:241]
	v_pk_mul_f32 v[80:81], v[80:81], v[242:243]
	v_pk_mul_f32 v[74:75], v[74:75], v[244:245]
	v_pk_mul_f32 v[76:77], v[76:77], v[230:231]
	v_cvt_pk_bf16_f32 v232, v78, v79
	v_cvt_pk_bf16_f32 v233, v80, v81
	v_cvt_pk_bf16_f32 v234, v74, v75
	v_cvt_pk_bf16_f32 v235, v76, v77
	global_store_dwordx4 v218, v[232:235], s[96:97]
	s_add_u32 s96, s96, 0x1000
	s_addc_u32 s97, s97, 0
	v_pk_mul_f32 v[224:225], v[70:71], v[220:221]
	v_pk_mul_f32 v[226:227], v[72:73], v[220:221]
	v_pk_mul_f32 v[228:229], v[66:67], v[220:221]
	v_pk_mul_f32 v[230:231], v[68:69], v[220:221]
	v_min_f32_e32 v224, 0x42fc0000, v224
	v_min_f32_e32 v225, 0x42fc0000, v225
	v_min_f32_e32 v226, 0x42fc0000, v226
	v_min_f32_e32 v227, 0x42fc0000, v227
	v_exp_f32_e32 v224, v224
	v_exp_f32_e32 v225, v225
	v_exp_f32_e32 v226, v226
	v_exp_f32_e32 v227, v227
	v_exp_f32_e32 v228, v228
	v_exp_f32_e32 v229, v229
	v_exp_f32_e32 v230, v230
	v_exp_f32_e32 v231, v231
	v_pk_add_f32 v[224:225], v[224:225], v[222:223]
	v_pk_add_f32 v[226:227], v[226:227], v[222:223]
	v_pk_add_f32 v[228:229], v[228:229], v[222:223]
	v_pk_add_f32 v[230:231], v[230:231], v[222:223]
	v_rcp_f32_e32 v228, v228
	v_rcp_f32_e32 v229, v229
	v_rcp_f32_e32 v230, v230
	v_rcp_f32_e32 v231, v231
	v_sub_u32_e32 v240, 0x7ef311c7, v224
	v_sub_u32_e32 v241, 0x7ef311c7, v225
	v_sub_u32_e32 v242, 0x7ef311c7, v226
	v_sub_u32_e32 v243, 0x7ef311c7, v227
	v_pk_fma_f32 v[246:247], v[224:225], v[240:241], v[222:223] neg_lo:[1,0,0] neg_hi:[1,0,0]
	v_pk_fma_f32 v[248:249], v[226:227], v[242:243], v[222:223] neg_lo:[1,0,0] neg_hi:[1,0,0]
	v_pk_fma_f32 v[240:241], v[240:241], v[246:247], v[240:241]
	v_pk_fma_f32 v[242:243], v[242:243], v[248:249], v[242:243]
	v_pk_fma_f32 v[246:247], v[224:225], v[240:241], v[222:223] neg_lo:[1,0,0] neg_hi:[1,0,0]
	v_pk_fma_f32 v[248:249], v[226:227], v[242:243], v[222:223] neg_lo:[1,0,0] neg_hi:[1,0,0]
	v_pk_fma_f32 v[240:241], v[240:241], v[246:247], v[240:241]
	v_pk_fma_f32 v[242:243], v[242:243], v[248:249], v[242:243]
	v_pk_fma_f32 v[246:247], v[224:225], v[240:241], v[222:223] neg_lo:[1,0,0] neg_hi:[1,0,0]
	v_pk_fma_f32 v[248:249], v[226:227], v[242:243], v[222:223] neg_lo:[1,0,0] neg_hi:[1,0,0]
	v_pk_fma_f32 v[240:241], v[240:241], v[246:247], v[240:241]
	v_pk_fma_f32 v[242:243], v[242:243], v[248:249], v[242:243]
	v_pk_mul_f32 v[70:71], v[70:71], v[240:241]
	v_pk_mul_f32 v[72:73], v[72:73], v[242:243]
	v_pk_mul_f32 v[66:67], v[66:67], v[228:229]
	v_pk_mul_f32 v[68:69], v[68:69], v[230:231]
	v_cvt_pk_bf16_f32 v236, v70, v71
	v_cvt_pk_bf16_f32 v237, v72, v73
	v_cvt_pk_bf16_f32 v238, v66, v67
	v_cvt_pk_bf16_f32 v239, v68, v69
	global_store_dwordx4 v218, v[236:239], s[96:97]
	s_add_u32 s96, s96, 0x1000
	s_addc_u32 s97, s97, 0
	s_add_u32 s96, s96, 0x8000
	s_addc_u32 s97, s97, 0
	v_pk_mul_f32 v[224:225], v[62:63], v[220:221]
	v_pk_mul_f32 v[226:227], v[64:65], v[220:221]
	v_pk_mul_f32 v[228:229], v[58:59], v[220:221]
	v_pk_mul_f32 v[230:231], v[60:61], v[220:221]
	v_min_f32_e32 v224, 0x42fc0000, v224
	v_min_f32_e32 v225, 0x42fc0000, v225
	v_min_f32_e32 v226, 0x42fc0000, v226
	v_min_f32_e32 v227, 0x42fc0000, v227
	v_min_f32_e32 v228, 0x42fc0000, v228
	v_min_f32_e32 v229, 0x42fc0000, v229
	v_exp_f32_e32 v224, v224
	v_exp_f32_e32 v225, v225
	v_exp_f32_e32 v226, v226
	v_exp_f32_e32 v227, v227
	v_exp_f32_e32 v228, v228
	v_exp_f32_e32 v229, v229
	v_exp_f32_e32 v230, v230
	v_exp_f32_e32 v231, v231
	v_pk_add_f32 v[224:225], v[224:225], v[222:223]
	v_pk_add_f32 v[226:227], v[226:227], v[222:223]
	v_pk_add_f32 v[228:229], v[228:229], v[222:223]
	v_pk_add_f32 v[230:231], v[230:231], v[222:223]
	v_rcp_f32_e32 v230, v230
	v_rcp_f32_e32 v231, v231
	v_sub_u32_e32 v240, 0x7ef311c7, v224
	v_sub_u32_e32 v241, 0x7ef311c7, v225
	v_sub_u32_e32 v242, 0x7ef311c7, v226
	v_sub_u32_e32 v243, 0x7ef311c7, v227
	v_sub_u32_e32 v244, 0x7ef311c7, v228
	v_sub_u32_e32 v245, 0x7ef311c7, v229
	v_pk_fma_f32 v[246:247], v[224:225], v[240:241], v[222:223] neg_lo:[1,0,0] neg_hi:[1,0,0]
	v_pk_fma_f32 v[248:249], v[226:227], v[242:243], v[222:223] neg_lo:[1,0,0] neg_hi:[1,0,0]
	v_pk_fma_f32 v[250:251], v[228:229], v[244:245], v[222:223] neg_lo:[1,0,0] neg_hi:[1,0,0]
; __device__ __forceinline__ unsigned cvt_pk_bf16(float lo, float hi) { unsigned r; asm volatile("v_cvt_pk_bf16_f32 %0, %1, %2" : "=v"(r) : "v"(lo), "v"(hi)); return r; }
; __device__ __forceinline__ float silu_f(float x) { return x * __builtin_amdgcn_rcpf(1.0f + __builtin_amdgcn_exp2f(-x * LOG2E)); }
;     __device__ __forceinline__ void operator()(const f32x4 (&acc)[2][2][4][2], const pg8::Unit& u, int wr, int wc, int fr, int fq, const LAS float* tab) const {
;     ...
;                 for (int bj = 0; bj < 2; ++bj) {
;                     f32x4 v0 = acc[ai][bj][m][0], v1 = acc[ai][bj][m][1];
;                     if (kind == 1) {
; #pragma unroll
;                         for (int e = 0; e < 4; ++e) { v0[e] = silu_f(v0[e]); v1[e] = silu_f(v1[e]); }
;                     } else if (kind == 2) { v0 = v0 * QSCALE; v1 = v1 * QSCALE; }
;                     else if (kind == 3) {
; #pragma unroll
;                         for (int e = 0; e < 4; ++e) { s1 += v0[e] + v1[e]; s2 += v0[e] * v0[e] + v1[e] * v1[e]; }
;                     } else if (kind == 4) {
;                         v0 = v0 * f2; v1 = v1 * f2;
; #pragma unroll
;                         for (int e = 0; e < 4; ++e) s2 += v0[e] * v0[e] + v1[e] * v1[e];
;                     }
;                     u32x4 w; w.x = cvt_pk_bf16(v0[0], v0[1]); w.y = cvt_pk_bf16(v0[2], v0[3]); w.z = cvt_pk_bf16(v1[0], v1[1]); w.w = cvt_pk_bf16(v1[2], v1[3]);
;                     *(u32x4*)(rowp + bj * bjstep) = w;
	v_pk_fma_f32 v[240:241], v[240:241], v[246:247], v[240:241]
	v_pk_fma_f32 v[242:243], v[242:243], v[248:249], v[242:243]
	v_pk_fma_f32 v[244:245], v[244:245], v[250:251], v[244:245]
	v_pk_fma_f32 v[246:247], v[224:225], v[240:241], v[222:223] neg_lo:[1,0,0] neg_hi:[1,0,0]
	v_pk_fma_f32 v[248:249], v[226:227], v[242:243], v[222:223] neg_lo:[1,0,0] neg_hi:[1,0,0]
	v_pk_fma_f32 v[250:251], v[228:229], v[244:245], v[222:223] neg_lo:[1,0,0] neg_hi:[1,0,0]
	v_pk_fma_f32 v[240:241], v[240:241], v[246:247], v[240:241]
	v_pk_fma_f32 v[242:243], v[242:243], v[248:249], v[242:243]
	v_pk_fma_f32 v[244:245], v[244:245], v[250:251], v[244:245]
	v_pk_fma_f32 v[246:247], v[224:225], v[240:241], v[222:223] neg_lo:[1,0,0] neg_hi:[1,0,0]
	v_pk_fma_f32 v[248:249], v[226:227], v[242:243], v[222:223] neg_lo:[1,0,0] neg_hi:[1,0,0]
	v_pk_fma_f32 v[250:251], v[228:229], v[244:245], v[222:223] neg_lo:[1,0,0] neg_hi:[1,0,0]
	v_pk_fma_f32 v[240:241], v[240:241], v[246:247], v[240:241]
	v_pk_fma_f32 v[242:243], v[242:243], v[248:249], v[242:243]
	v_pk_fma_f32 v[244:245], v[244:245], v[250:251], v[244:245]
	v_pk_mul_f32 v[62:63], v[62:63], v[240:241]
	v_pk_mul_f32 v[64:65], v[64:65], v[242:243]
	v_pk_mul_f32 v[58:59], v[58:59], v[244:245]
	v_pk_mul_f32 v[60:61], v[60:61], v[230:231]
	v_cvt_pk_bf16_f32 v232, v62, v63
	v_cvt_pk_bf16_f32 v233, v64, v65
	v_cvt_pk_bf16_f32 v234, v58, v59
	v_cvt_pk_bf16_f32 v235, v60, v61
	global_store_dwordx4 v218, v[232:235], s[96:97]
	s_add_u32 s96, s96, 0x1000
	s_addc_u32 s97, s97, 0
	v_pk_mul_f32 v[224:225], v[54:55], v[220:221]
	v_pk_mul_f32 v[226:227], v[56:57], v[220:221]
	v_pk_mul_f32 v[228:229], v[50:51], v[220:221]
	v_pk_mul_f32 v[230:231], v[52:53], v[220:221]
	v_min_f32_e32 v224, 0x42fc0000, v224
	v_min_f32_e32 v225, 0x42fc0000, v225
	v_min_f32_e32 v226, 0x42fc0000, v226
	v_min_f32_e32 v227, 0x42fc0000, v227
	v_exp_f32_e32 v224, v224
	v_exp_f32_e32 v225, v225
	v_exp_f32_e32 v226, v226
	v_exp_f32_e32 v227, v227
	v_exp_f32_e32 v228, v228
	v_exp_f32_e32 v229, v229
	v_exp_f32_e32 v230, v230
	v_exp_f32_e32 v231, v231
	v_pk_add_f32 v[224:225], v[224:225], v[222:223]
	v_pk_add_f32 v[226:227], v[226:227], v[222:223]
	v_pk_add_f32 v[228:229], v[228:229], v[222:223]
	v_pk_add_f32 v[230:231], v[230:231], v[222:223]
	v_rcp_f32_e32 v228, v228
	v_rcp_f32_e32 v229, v229
	v_rcp_f32_e32 v230, v230
	v_rcp_f32_e32 v231, v231
	v_sub_u32_e32 v240, 0x7ef311c7, v224
	v_sub_u32_e32 v241, 0x7ef311c7, v225
	v_sub_u32_e32 v242, 0x7ef311c7, v226
	v_sub_u32_e32 v243, 0x7ef311c7, v227
	v_pk_fma_f32 v[246:247], v[224:225], v[240:241], v[222:223] neg_lo:[1,0,0] neg_hi:[1,0,0]
	v_pk_fma_f32 v[248:249], v[226:227], v[242:243], v[222:223] neg_lo:[1,0,0] neg_hi:[1,0,0]
	v_pk_fma_f32 v[240:241], v[240:241], v[246:247], v[240:241]
	v_pk_fma_f32 v[242:243], v[242:243], v[248:249], v[242:243]
	v_pk_fma_f32 v[246:247], v[224:225], v[240:241], v[222:223] neg_lo:[1,0,0] neg_hi:[1,0,0]
	v_pk_fma_f32 v[248:249], v[226:227], v[242:243], v[222:223] neg_lo:[1,0,0] neg_hi:[1,0,0]
	v_pk_fma_f32 v[240:241], v[240:241], v[246:247], v[240:241]
	v_pk_fma_f32 v[242:243], v[242:243], v[248:249], v[242:243]
	v_pk_fma_f32 v[246:247], v[224:225], v[240:241], v[222:223] neg_lo:[1,0,0] neg_hi:[1,0,0]
	v_pk_fma_f32 v[248:249], v[226:227], v[242:243], v[222:223] neg_lo:[1,0,0] neg_hi:[1,0,0]
	v_pk_fma_f32 v[240:241], v[240:241], v[246:247], v[240:241]
	v_pk_fma_f32 v[242:243], v[242:243], v[248:249], v[242:243]
	v_pk_mul_f32 v[54:55], v[54:55], v[240:241]
	v_pk_mul_f32 v[56:57], v[56:57], v[242:243]
	v_pk_mul_f32 v[50:51], v[50:51], v[228:229]
	v_pk_mul_f32 v[52:53], v[52:53], v[230:231]
	v_cvt_pk_bf16_f32 v236, v54, v55
	v_cvt_pk_bf16_f32 v237, v56, v57
	v_cvt_pk_bf16_f32 v238, v50, v51
	v_cvt_pk_bf16_f32 v239, v52, v53
	global_store_dwordx4 v218, v[236:239], s[96:97]
	s_add_u32 s96, s96, 0x1000
	s_addc_u32 s97, s97, 0
	v_pk_mul_f32 v[224:225], v[46:47], v[220:221]
	v_pk_mul_f32 v[226:227], v[48:49], v[220:221]
	v_pk_mul_f32 v[228:229], v[42:43], v[220:221]
	v_pk_mul_f32 v[230:231], v[44:45], v[220:221]
	v_min_f32_e32 v224, 0x42fc0000, v224
	v_min_f32_e32 v225, 0x42fc0000, v225
	v_min_f32_e32 v226, 0x42fc0000, v226
	v_min_f32_e32 v227, 0x42fc0000, v227
	v_min_f32_e32 v228, 0x42fc0000, v228
	v_min_f32_e32 v229, 0x42fc0000, v229
	v_exp_f32_e32 v224, v224
	v_exp_f32_e32 v225, v225
	v_exp_f32_e32 v226, v226
	v_exp_f32_e32 v227, v227
	v_exp_f32_e32 v228, v228
	v_exp_f32_e32 v229, v229
	v_exp_f32_e32 v230, v230
	v_exp_f32_e32 v231, v231
	v_pk_add_f32 v[224:225], v[224:225], v[222:223]
	v_pk_add_f32 v[226:227], v[226:227], v[222:223]
	v_pk_add_f32 v[228:229], v[228:229], v[222:223]
	v_pk_add_f32 v[230:231], v[230:231], v[222:223]
	v_rcp_f32_e32 v230, v230
	v_rcp_f32_e32 v231, v231
	v_sub_u32_e32 v240, 0x7ef311c7, v224
	v_sub_u32_e32 v241, 0x7ef311c7, v225
	v_sub_u32_e32 v242, 0x7ef311c7, v226
	v_sub_u32_e32 v243, 0x7ef311c7, v227
	v_sub_u32_e32 v244, 0x7ef311c7, v228
	v_sub_u32_e32 v245, 0x7ef311c7, v229
	v_pk_fma_f32 v[246:247], v[224:225], v[240:241], v[222:223] neg_lo:[1,0,0] neg_hi:[1,0,0]
	v_pk_fma_f32 v[248:249], v[226:227], v[242:243], v[222:223] neg_lo:[1,0,0] neg_hi:[1,0,0]
	v_pk_fma_f32 v[250:251], v[228:229], v[244:245], v[222:223] neg_lo:[1,0,0] neg_hi:[1,0,0]
	v_pk_fma_f32 v[240:241], v[240:241], v[246:247], v[240:241]
	v_pk_fma_f32 v[242:243], v[242:243], v[248:249], v[242:243]
	v_pk_fma_f32 v[244:245], v[244:245], v[250:251], v[244:245]
	v_pk_fma_f32 v[246:247], v[224:225], v[240:241], v[222:223] neg_lo:[1,0,0] neg_hi:[1,0,0]
	v_pk_fma_f32 v[248:249], v[226:227], v[242:243], v[222:223] neg_lo:[1,0,0] neg_hi:[1,0,0]
	v_pk_fma_f32 v[250:251], v[228:229], v[244:245], v[222:223] neg_lo:[1,0,0] neg_hi:[1,0,0]
; __device__ __forceinline__ unsigned cvt_pk_bf16(float lo, float hi) { unsigned r; asm volatile("v_cvt_pk_bf16_f32 %0, %1, %2" : "=v"(r) : "v"(lo), "v"(hi)); return r; }
; __device__ __forceinline__ float silu_f(float x) { return x * __builtin_amdgcn_rcpf(1.0f + __builtin_amdgcn_exp2f(-x * LOG2E)); }
;     __device__ __forceinline__ void operator()(const f32x4 (&acc)[2][2][4][2], const pg8::Unit& u, int wr, int wc, int fr, int fq, const LAS float* tab) const {
;     ...
;                 for (int bj = 0; bj < 2; ++bj) {
;                     f32x4 v0 = acc[ai][bj][m][0], v1 = acc[ai][bj][m][1];
;                     if (kind == 1) {
; #pragma unroll
;                         for (int e = 0; e < 4; ++e) { v0[e] = silu_f(v0[e]); v1[e] = silu_f(v1[e]); }
;                     } else if (kind == 2) { v0 = v0 * QSCALE; v1 = v1 * QSCALE; }
;                     else if (kind == 3) {
; #pragma unroll
;                         for (int e = 0; e < 4; ++e) { s1 += v0[e] + v1[e]; s2 += v0[e] * v0[e] + v1[e] * v1[e]; }
;                     } else if (kind == 4) {
;                         v0 = v0 * f2; v1 = v1 * f2;
; #pragma unroll
;                         for (int e = 0; e < 4; ++e) s2 += v0[e] * v0[e] + v1[e] * v1[e];
;                     }
;                     u32x4 w; w.x = cvt_pk_bf16(v0[0], v0[1]); w.y = cvt_pk_bf16(v0[2], v0[3]); w.z = cvt_pk_bf16(v1[0], v1[1]); w.w = cvt_pk_bf16(v1[2], v1[3]);
;                     *(u32x4*)(rowp + bj * bjstep) = w;
	v_pk_fma_f32 v[240:241], v[240:241], v[246:247], v[240:241]
	v_pk_fma_f32 v[242:243], v[242:243], v[248:249], v[242:243]
	v_pk_fma_f32 v[244:245], v[244:245], v[250:251], v[244:245]
	v_pk_fma_f32 v[246:247], v[224:225], v[240:241], v[222:223] neg_lo:[1,0,0] neg_hi:[1,0,0]
	v_pk_fma_f32 v[248:249], v[226:227], v[242:243], v[222:223] neg_lo:[1,0,0] neg_hi:[1,0,0]
	v_pk_fma_f32 v[250:251], v[228:229], v[244:245], v[222:223] neg_lo:[1,0,0] neg_hi:[1,0,0]
	v_pk_fma_f32 v[240:241], v[240:241], v[246:247], v[240:241]
	v_pk_fma_f32 v[242:243], v[242:243], v[248:249], v[242:243]
	v_pk_fma_f32 v[244:245], v[244:245], v[250:251], v[244:245]
	v_pk_mul_f32 v[46:47], v[46:47], v[240:241]
	v_pk_mul_f32 v[48:49], v[48:49], v[242:243]
	v_pk_mul_f32 v[42:43], v[42:43], v[244:245]
	v_pk_mul_f32 v[44:45], v[44:45], v[230:231]
	v_cvt_pk_bf16_f32 v232, v46, v47
	v_cvt_pk_bf16_f32 v233, v48, v49
	v_cvt_pk_bf16_f32 v234, v42, v43
	v_cvt_pk_bf16_f32 v235, v44, v45
	global_store_dwordx4 v218, v[232:235], s[96:97]
	s_add_u32 s96, s96, 0x1000
	s_addc_u32 s97, s97, 0
	v_pk_mul_f32 v[224:225], v[38:39], v[220:221]
	v_pk_mul_f32 v[226:227], v[40:41], v[220:221]
	v_pk_mul_f32 v[228:229], v[34:35], v[220:221]
	v_pk_mul_f32 v[230:231], v[36:37], v[220:221]
	v_min_f32_e32 v224, 0x42fc0000, v224
	v_min_f32_e32 v225, 0x42fc0000, v225
	v_min_f32_e32 v226, 0x42fc0000, v226
	v_min_f32_e32 v227, 0x42fc0000, v227
	v_exp_f32_e32 v224, v224
	v_exp_f32_e32 v225, v225
	v_exp_f32_e32 v226, v226
	v_exp_f32_e32 v227, v227
	v_exp_f32_e32 v228, v228
	v_exp_f32_e32 v229, v229
	v_exp_f32_e32 v230, v230
	v_exp_f32_e32 v231, v231
	v_pk_add_f32 v[224:225], v[224:225], v[222:223]
	v_pk_add_f32 v[226:227], v[226:227], v[222:223]
	v_pk_add_f32 v[228:229], v[228:229], v[222:223]
	v_pk_add_f32 v[230:231], v[230:231], v[222:223]
	v_rcp_f32_e32 v228, v228
	v_rcp_f32_e32 v229, v229
	v_rcp_f32_e32 v230, v230
	v_rcp_f32_e32 v231, v231
	v_sub_u32_e32 v240, 0x7ef311c7, v224
	v_sub_u32_e32 v241, 0x7ef311c7, v225
	v_sub_u32_e32 v242, 0x7ef311c7, v226
	v_sub_u32_e32 v243, 0x7ef311c7, v227
	v_pk_fma_f32 v[246:247], v[224:225], v[240:241], v[222:223] neg_lo:[1,0,0] neg_hi:[1,0,0]
	v_pk_fma_f32 v[248:249], v[226:227], v[242:243], v[222:223] neg_lo:[1,0,0] neg_hi:[1,0,0]
	v_pk_fma_f32 v[240:241], v[240:241], v[246:247], v[240:241]
	v_pk_fma_f32 v[242:243], v[242:243], v[248:249], v[242:243]
	v_pk_fma_f32 v[246:247], v[224:225], v[240:241], v[222:223] neg_lo:[1,0,0] neg_hi:[1,0,0]
	v_pk_fma_f32 v[248:249], v[226:227], v[242:243], v[222:223] neg_lo:[1,0,0] neg_hi:[1,0,0]
	v_pk_fma_f32 v[240:241], v[240:241], v[246:247], v[240:241]
	v_pk_fma_f32 v[242:243], v[242:243], v[248:249], v[242:243]
	v_pk_fma_f32 v[246:247], v[224:225], v[240:241], v[222:223] neg_lo:[1,0,0] neg_hi:[1,0,0]
	v_pk_fma_f32 v[248:249], v[226:227], v[242:243], v[222:223] neg_lo:[1,0,0] neg_hi:[1,0,0]
	v_pk_fma_f32 v[240:241], v[240:241], v[246:247], v[240:241]
	v_pk_fma_f32 v[242:243], v[242:243], v[248:249], v[242:243]
	v_pk_mul_f32 v[38:39], v[38:39], v[240:241]
	v_pk_mul_f32 v[40:41], v[40:41], v[242:243]
	v_pk_mul_f32 v[34:35], v[34:35], v[228:229]
	v_pk_mul_f32 v[36:37], v[36:37], v[230:231]
	v_cvt_pk_bf16_f32 v236, v38, v39
	v_cvt_pk_bf16_f32 v237, v40, v41
	v_cvt_pk_bf16_f32 v238, v34, v35
	v_cvt_pk_bf16_f32 v239, v36, v37
	global_store_dwordx4 v218, v[236:239], s[96:97]
	s_add_u32 s96, s96, 0x1000
	s_addc_u32 s97, s97, 0
	v_pk_mul_f32 v[224:225], v[30:31], v[220:221]
	v_pk_mul_f32 v[226:227], v[32:33], v[220:221]
	v_pk_mul_f32 v[228:229], v[26:27], v[220:221]
	v_pk_mul_f32 v[230:231], v[28:29], v[220:221]
	v_min_f32_e32 v224, 0x42fc0000, v224
	v_min_f32_e32 v225, 0x42fc0000, v225
	v_min_f32_e32 v226, 0x42fc0000, v226
	v_min_f32_e32 v227, 0x42fc0000, v227
	v_min_f32_e32 v228, 0x42fc0000, v228
	v_min_f32_e32 v229, 0x42fc0000, v229
	v_exp_f32_e32 v224, v224
	v_exp_f32_e32 v225, v225
	v_exp_f32_e32 v226, v226
	v_exp_f32_e32 v227, v227
	v_exp_f32_e32 v228, v228
	v_exp_f32_e32 v229, v229
	v_exp_f32_e32 v230, v230
	v_exp_f32_e32 v231, v231
	v_pk_add_f32 v[224:225], v[224:225], v[222:223]
	v_pk_add_f32 v[226:227], v[226:227], v[222:223]
	v_pk_add_f32 v[228:229], v[228:229], v[222:223]
	v_pk_add_f32 v[230:231], v[230:231], v[222:223]
	v_rcp_f32_e32 v230, v230
	v_rcp_f32_e32 v231, v231
	v_sub_u32_e32 v240, 0x7ef311c7, v224
	v_sub_u32_e32 v241, 0x7ef311c7, v225
	v_sub_u32_e32 v242, 0x7ef311c7, v226
	v_sub_u32_e32 v243, 0x7ef311c7, v227
	v_sub_u32_e32 v244, 0x7ef311c7, v228
	v_sub_u32_e32 v245, 0x7ef311c7, v229
	v_pk_fma_f32 v[246:247], v[224:225], v[240:241], v[222:223] neg_lo:[1,0,0] neg_hi:[1,0,0]
	v_pk_fma_f32 v[248:249], v[226:227], v[242:243], v[222:223] neg_lo:[1,0,0] neg_hi:[1,0,0]
	v_pk_fma_f32 v[250:251], v[228:229], v[244:245], v[222:223] neg_lo:[1,0,0] neg_hi:[1,0,0]
	v_pk_fma_f32 v[240:241], v[240:241], v[246:247], v[240:241]
	v_pk_fma_f32 v[242:243], v[242:243], v[248:249], v[242:243]
	v_pk_fma_f32 v[244:245], v[244:245], v[250:251], v[244:245]
	v_pk_fma_f32 v[246:247], v[224:225], v[240:241], v[222:223] neg_lo:[1,0,0] neg_hi:[1,0,0]
	v_pk_fma_f32 v[248:249], v[226:227], v[242:243], v[222:223] neg_lo:[1,0,0] neg_hi:[1,0,0]
	v_pk_fma_f32 v[250:251], v[228:229], v[244:245], v[222:223] neg_lo:[1,0,0] neg_hi:[1,0,0]
	v_pk_fma_f32 v[240:241], v[240:241], v[246:247], v[240:241]
	v_pk_fma_f32 v[242:243], v[242:243], v[248:249], v[242:243]
	v_pk_fma_f32 v[244:245], v[244:245], v[250:251], v[244:245]
	v_pk_fma_f32 v[246:247], v[224:225], v[240:241], v[222:223] neg_lo:[1,0,0] neg_hi:[1,0,0]
	v_pk_fma_f32 v[248:249], v[226:227], v[242:243], v[222:223] neg_lo:[1,0,0] neg_hi:[1,0,0]
	v_pk_fma_f32 v[250:251], v[228:229], v[244:245], v[222:223] neg_lo:[1,0,0] neg_hi:[1,0,0]
; __device__ __forceinline__ unsigned cvt_pk_bf16(float lo, float hi) { unsigned r; asm volatile("v_cvt_pk_bf16_f32 %0, %1, %2" : "=v"(r) : "v"(lo), "v"(hi)); return r; }
; __device__ __forceinline__ float silu_f(float x) { return x * __builtin_amdgcn_rcpf(1.0f + __builtin_amdgcn_exp2f(-x * LOG2E)); }
;     __device__ __forceinline__ void operator()(const f32x4 (&acc)[2][2][4][2], const pg8::Unit& u, int wr, int wc, int fr, int fq, const LAS float* tab) const {
;     ...
;                 for (int bj = 0; bj < 2; ++bj) {
;                     f32x4 v0 = acc[ai][bj][m][0], v1 = acc[ai][bj][m][1];
;                     if (kind == 1) {
; #pragma unroll
;                         for (int e = 0; e < 4; ++e) { v0[e] = silu_f(v0[e]); v1[e] = silu_f(v1[e]); }
;                     } else if (kind == 2) { v0 = v0 * QSCALE; v1 = v1 * QSCALE; }
;                     else if (kind == 3) {
; #pragma unroll
;                         for (int e = 0; e < 4; ++e) { s1 += v0[e] + v1[e]; s2 += v0[e] * v0[e] + v1[e] * v1[e]; }
;                     } else if (kind == 4) {
;                         v0 = v0 * f2; v1 = v1 * f2;
; #pragma unroll
;                         for (int e = 0; e < 4; ++e) s2 += v0[e] * v0[e] + v1[e] * v1[e];
;                     }
;                     u32x4 w; w.x = cvt_pk_bf16(v0[0], v0[1]); w.y = cvt_pk_bf16(v0[2], v0[3]); w.z = cvt_pk_bf16(v1[0], v1[1]); w.w = cvt_pk_bf16(v1[2], v1[3]);
;                     *(u32x4*)(rowp + bj * bjstep) = w;
	v_pk_fma_f32 v[240:241], v[240:241], v[246:247], v[240:241]
	v_pk_fma_f32 v[242:243], v[242:243], v[248:249], v[242:243]
	v_pk_fma_f32 v[244:245], v[244:245], v[250:251], v[244:245]
	v_pk_mul_f32 v[30:31], v[30:31], v[240:241]
	v_pk_mul_f32 v[32:33], v[32:33], v[242:243]
	v_pk_mul_f32 v[26:27], v[26:27], v[244:245]
	v_pk_mul_f32 v[28:29], v[28:29], v[230:231]
	v_cvt_pk_bf16_f32 v232, v30, v31
	v_cvt_pk_bf16_f32 v233, v32, v33
	v_cvt_pk_bf16_f32 v234, v26, v27
	v_cvt_pk_bf16_f32 v235, v28, v29
	global_store_dwordx4 v218, v[232:235], s[96:97]
	s_add_u32 s96, s96, 0x1000
	s_addc_u32 s97, s97, 0
	v_pk_mul_f32 v[224:225], v[22:23], v[220:221]
	v_pk_mul_f32 v[226:227], v[24:25], v[220:221]
	v_pk_mul_f32 v[228:229], v[18:19], v[220:221]
	v_pk_mul_f32 v[230:231], v[20:21], v[220:221]
	v_min_f32_e32 v224, 0x42fc0000, v224
	v_min_f32_e32 v225, 0x42fc0000, v225
	v_min_f32_e32 v226, 0x42fc0000, v226
	v_min_f32_e32 v227, 0x42fc0000, v227
	v_exp_f32_e32 v224, v224
	v_exp_f32_e32 v225, v225
	v_exp_f32_e32 v226, v226
	v_exp_f32_e32 v227, v227
	v_exp_f32_e32 v228, v228
	v_exp_f32_e32 v229, v229
	v_exp_f32_e32 v230, v230
	v_exp_f32_e32 v231, v231
	v_pk_add_f32 v[224:225], v[224:225], v[222:223]
	v_pk_add_f32 v[226:227], v[226:227], v[222:223]
	v_pk_add_f32 v[228:229], v[228:229], v[222:223]
	v_pk_add_f32 v[230:231], v[230:231], v[222:223]
	v_rcp_f32_e32 v228, v228
	v_rcp_f32_e32 v229, v229
	v_rcp_f32_e32 v230, v230
	v_rcp_f32_e32 v231, v231
	v_sub_u32_e32 v240, 0x7ef311c7, v224
	v_sub_u32_e32 v241, 0x7ef311c7, v225
	v_sub_u32_e32 v242, 0x7ef311c7, v226
	v_sub_u32_e32 v243, 0x7ef311c7, v227
	v_pk_fma_f32 v[246:247], v[224:225], v[240:241], v[222:223] neg_lo:[1,0,0] neg_hi:[1,0,0]
	v_pk_fma_f32 v[248:249], v[226:227], v[242:243], v[222:223] neg_lo:[1,0,0] neg_hi:[1,0,0]
	v_pk_fma_f32 v[240:241], v[240:241], v[246:247], v[240:241]
	v_pk_fma_f32 v[242:243], v[242:243], v[248:249], v[242:243]
	v_pk_fma_f32 v[246:247], v[224:225], v[240:241], v[222:223] neg_lo:[1,0,0] neg_hi:[1,0,0]
	v_pk_fma_f32 v[248:249], v[226:227], v[242:243], v[222:223] neg_lo:[1,0,0] neg_hi:[1,0,0]
	v_pk_fma_f32 v[240:241], v[240:241], v[246:247], v[240:241]
	v_pk_fma_f32 v[242:243], v[242:243], v[248:249], v[242:243]
	v_pk_fma_f32 v[246:247], v[224:225], v[240:241], v[222:223] neg_lo:[1,0,0] neg_hi:[1,0,0]
	v_pk_fma_f32 v[248:249], v[226:227], v[242:243], v[222:223] neg_lo:[1,0,0] neg_hi:[1,0,0]
	v_pk_fma_f32 v[240:241], v[240:241], v[246:247], v[240:241]
	v_pk_fma_f32 v[242:243], v[242:243], v[248:249], v[242:243]
	v_pk_mul_f32 v[22:23], v[22:23], v[240:241]
	v_pk_mul_f32 v[24:25], v[24:25], v[242:243]
	v_pk_mul_f32 v[18:19], v[18:19], v[228:229]
	v_pk_mul_f32 v[20:21], v[20:21], v[230:231]
	v_cvt_pk_bf16_f32 v236, v22, v23
	v_cvt_pk_bf16_f32 v237, v24, v25
	v_cvt_pk_bf16_f32 v238, v18, v19
	v_cvt_pk_bf16_f32 v239, v20, v21
	global_store_dwordx4 v218, v[236:239], s[96:97]
	s_add_u32 s96, s96, 0x1000
	s_addc_u32 s97, s97, 0
	v_pk_mul_f32 v[224:225], v[14:15], v[220:221]
	v_pk_mul_f32 v[226:227], v[16:17], v[220:221]
	v_pk_mul_f32 v[228:229], v[10:11], v[220:221]
	v_pk_mul_f32 v[230:231], v[12:13], v[220:221]
	v_min_f32_e32 v224, 0x42fc0000, v224
	v_min_f32_e32 v225, 0x42fc0000, v225
	v_min_f32_e32 v226, 0x42fc0000, v226
	v_min_f32_e32 v227, 0x42fc0000, v227
	v_min_f32_e32 v228, 0x42fc0000, v228
	v_min_f32_e32 v229, 0x42fc0000, v229
	v_exp_f32_e32 v224, v224
	v_exp_f32_e32 v225, v225
	v_exp_f32_e32 v226, v226
	v_exp_f32_e32 v227, v227
	v_exp_f32_e32 v228, v228
	v_exp_f32_e32 v229, v229
	v_exp_f32_e32 v230, v230
	v_exp_f32_e32 v231, v231
	v_pk_add_f32 v[224:225], v[224:225], v[222:223]
	v_pk_add_f32 v[226:227], v[226:227], v[222:223]
	v_pk_add_f32 v[228:229], v[228:229], v[222:223]
	v_pk_add_f32 v[230:231], v[230:231], v[222:223]
	v_rcp_f32_e32 v230, v230
	v_rcp_f32_e32 v231, v231
	v_sub_u32_e32 v240, 0x7ef311c7, v224
	v_sub_u32_e32 v241, 0x7ef311c7, v225
	v_sub_u32_e32 v242, 0x7ef311c7, v226
	v_sub_u32_e32 v243, 0x7ef311c7, v227
	v_sub_u32_e32 v244, 0x7ef311c7, v228
	v_sub_u32_e32 v245, 0x7ef311c7, v229
; __device__ __forceinline__ unsigned cvt_pk_bf16(float lo, float hi) { unsigned r; asm volatile("v_cvt_pk_bf16_f32 %0, %1, %2" : "=v"(r) : "v"(lo), "v"(hi)); return r; }
; __device__ __forceinline__ float silu_f(float x) { return x * __builtin_amdgcn_rcpf(1.0f + __builtin_amdgcn_exp2f(-x * LOG2E)); }
;     __device__ __forceinline__ void operator()(const f32x4 (&acc)[2][2][4][2], const pg8::Unit& u, int wr, int wc, int fr, int fq, const LAS float* tab) const {
;     ...
;                 for (int bj = 0; bj < 2; ++bj) {
;                     f32x4 v0 = acc[ai][bj][m][0], v1 = acc[ai][bj][m][1];
;                     if (kind == 1) {
; #pragma unroll
;                         for (int e = 0; e < 4; ++e) { v0[e] = silu_f(v0[e]); v1[e] = silu_f(v1[e]); }
;                     } else if (kind == 2) { v0 = v0 * QSCALE; v1 = v1 * QSCALE; }
;                     else if (kind == 3) {
; #pragma unroll
;                         for (int e = 0; e < 4; ++e) { s1 += v0[e] + v1[e]; s2 += v0[e] * v0[e] + v1[e] * v1[e]; }
;                     } else if (kind == 4) {
;                         v0 = v0 * f2; v1 = v1 * f2;
; #pragma unroll
;                         for (int e = 0; e < 4; ++e) s2 += v0[e] * v0[e] + v1[e] * v1[e];
;                     }
;                     u32x4 w; w.x = cvt_pk_bf16(v0[0], v0[1]); w.y = cvt_pk_bf16(v0[2], v0[3]); w.z = cvt_pk_bf16(v1[0], v1[1]); w.w = cvt_pk_bf16(v1[2], v1[3]);
;                     *(u32x4*)(rowp + bj * bjstep) = w;
	v_pk_fma_f32 v[246:247], v[224:225], v[240:241], v[222:223] neg_lo:[1,0,0] neg_hi:[1,0,0]
	v_pk_fma_f32 v[248:249], v[226:227], v[242:243], v[222:223] neg_lo:[1,0,0] neg_hi:[1,0,0]
	v_pk_fma_f32 v[250:251], v[228:229], v[244:245], v[222:223] neg_lo:[1,0,0] neg_hi:[1,0,0]
	v_pk_fma_f32 v[240:241], v[240:241], v[246:247], v[240:241]
	v_pk_fma_f32 v[242:243], v[242:243], v[248:249], v[242:243]
	v_pk_fma_f32 v[244:245], v[244:245], v[250:251], v[244:245]
	v_pk_fma_f32 v[246:247], v[224:225], v[240:241], v[222:223] neg_lo:[1,0,0] neg_hi:[1,0,0]
	v_pk_fma_f32 v[248:249], v[226:227], v[242:243], v[222:223] neg_lo:[1,0,0] neg_hi:[1,0,0]
	v_pk_fma_f32 v[250:251], v[228:229], v[244:245], v[222:223] neg_lo:[1,0,0] neg_hi:[1,0,0]
	v_pk_fma_f32 v[240:241], v[240:241], v[246:247], v[240:241]
	v_pk_fma_f32 v[242:243], v[242:243], v[248:249], v[242:243]
	v_pk_fma_f32 v[244:245], v[244:245], v[250:251], v[244:245]
	v_pk_fma_f32 v[246:247], v[224:225], v[240:241], v[222:223] neg_lo:[1,0,0] neg_hi:[1,0,0]
	v_pk_fma_f32 v[248:249], v[226:227], v[242:243], v[222:223] neg_lo:[1,0,0] neg_hi:[1,0,0]
	v_pk_fma_f32 v[250:251], v[228:229], v[244:245], v[222:223] neg_lo:[1,0,0] neg_hi:[1,0,0]
	v_pk_fma_f32 v[240:241], v[240:241], v[246:247], v[240:241]
	v_pk_fma_f32 v[242:243], v[242:243], v[248:249], v[242:243]
	v_pk_fma_f32 v[244:245], v[244:245], v[250:251], v[244:245]
	v_pk_mul_f32 v[14:15], v[14:15], v[240:241]
	v_pk_mul_f32 v[16:17], v[16:17], v[242:243]
	v_pk_mul_f32 v[10:11], v[10:11], v[244:245]
	v_pk_mul_f32 v[12:13], v[12:13], v[230:231]
	v_cvt_pk_bf16_f32 v232, v14, v15
	v_cvt_pk_bf16_f32 v233, v16, v17
	v_cvt_pk_bf16_f32 v234, v10, v11
	v_cvt_pk_bf16_f32 v235, v12, v13
	global_store_dwordx4 v218, v[232:235], s[96:97]
	s_add_u32 s96, s96, 0x1000
	s_addc_u32 s97, s97, 0
	v_pk_mul_f32 v[224:225], v[6:7], v[220:221]
	v_pk_mul_f32 v[226:227], v[8:9], v[220:221]
	v_pk_mul_f32 v[228:229], v[2:3], v[220:221]
	v_pk_mul_f32 v[230:231], v[4:5], v[220:221]
	v_min_f32_e32 v224, 0x42fc0000, v224
	v_min_f32_e32 v225, 0x42fc0000, v225
	v_min_f32_e32 v226, 0x42fc0000, v226
	v_min_f32_e32 v227, 0x42fc0000, v227
	v_exp_f32_e32 v224, v224
	v_exp_f32_e32 v225, v225
	v_exp_f32_e32 v226, v226
	v_exp_f32_e32 v227, v227
	v_exp_f32_e32 v228, v228
	v_exp_f32_e32 v229, v229
	v_exp_f32_e32 v230, v230
	v_exp_f32_e32 v231, v231
	v_pk_add_f32 v[224:225], v[224:225], v[222:223]
	v_pk_add_f32 v[226:227], v[226:227], v[222:223]
	v_pk_add_f32 v[228:229], v[228:229], v[222:223]
	v_pk_add_f32 v[230:231], v[230:231], v[222:223]
	v_rcp_f32_e32 v228, v228
	v_rcp_f32_e32 v229, v229
	v_rcp_f32_e32 v230, v230
	v_rcp_f32_e32 v231, v231
	v_sub_u32_e32 v240, 0x7ef311c7, v224
	v_sub_u32_e32 v241, 0x7ef311c7, v225
	v_sub_u32_e32 v242, 0x7ef311c7, v226
	v_sub_u32_e32 v243, 0x7ef311c7, v227
	v_pk_fma_f32 v[246:247], v[224:225], v[240:241], v[222:223] neg_lo:[1,0,0] neg_hi:[1,0,0]
	v_pk_fma_f32 v[248:249], v[226:227], v[242:243], v[222:223] neg_lo:[1,0,0] neg_hi:[1,0,0]
	v_pk_fma_f32 v[240:241], v[240:241], v[246:247], v[240:241]
	v_pk_fma_f32 v[242:243], v[242:243], v[248:249], v[242:243]
	v_pk_fma_f32 v[246:247], v[224:225], v[240:241], v[222:223] neg_lo:[1,0,0] neg_hi:[1,0,0]
	v_pk_fma_f32 v[248:249], v[226:227], v[242:243], v[222:223] neg_lo:[1,0,0] neg_hi:[1,0,0]
	v_pk_fma_f32 v[240:241], v[240:241], v[246:247], v[240:241]
	v_pk_fma_f32 v[242:243], v[242:243], v[248:249], v[242:243]
	v_pk_fma_f32 v[246:247], v[224:225], v[240:241], v[222:223] neg_lo:[1,0,0] neg_hi:[1,0,0]
	v_pk_fma_f32 v[248:249], v[226:227], v[242:243], v[222:223] neg_lo:[1,0,0] neg_hi:[1,0,0]
	v_pk_fma_f32 v[240:241], v[240:241], v[246:247], v[240:241]
	v_pk_fma_f32 v[242:243], v[242:243], v[248:249], v[242:243]
	v_pk_mul_f32 v[6:7], v[6:7], v[240:241]
	v_pk_mul_f32 v[8:9], v[8:9], v[242:243]
	v_pk_mul_f32 v[2:3], v[2:3], v[228:229]
	v_pk_mul_f32 v[4:5], v[4:5], v[230:231]
	v_cvt_pk_bf16_f32 v236, v6, v7
	v_cvt_pk_bf16_f32 v237, v8, v9
	v_cvt_pk_bf16_f32 v238, v2, v3
	v_cvt_pk_bf16_f32 v239, v4, v5
	global_store_dwordx4 v218, v[236:239], s[96:97]
	s_add_u32 s96, s96, 0x1000
	s_addc_u32 s97, s97, 0
	s_branch .LBB0_391
